# K-loop load segments: LDS-DMA loads issued before the segment's last block of ds_read_b128 instead of after it
# baseline (speedup 1.0000x reference)
.Lk1_body:
	ds_read_b128 v[130:133], v244
	ds_read_b128 v[134:137], v244 offset:1024
	ds_read_b128 v[138:141], v244 offset:2048
	ds_read_b128 v[142:145], v244 offset:3072
	ds_read_b128 v[170:173], v244 offset:16384
	ds_read_b128 v[174:177], v244 offset:17408
	ds_read_b128 v[202:205], v244 offset:18432
	ds_read_b128 v[206:209], v244 offset:19456
	s_add_i32 m0, s59, 0xc000
	s_nop 0
	global_load_lds_dwordx4 v166, s[8:9]
	s_add_i32 m0, s59, 0xe000
	s_nop 0
	global_load_lds_dwordx4 v168, s[8:9]
	ds_read_b128 v[210:213], v200
	ds_read_b128 v[216:219], v200 offset:1024
	ds_read_b128 v[220:223], v200 offset:2048
	ds_read_b128 v[224:227], v200 offset:3072
	ds_read_b128 v[228:231], v200 offset:4096
	ds_read_b128 v[232:235], v200 offset:5120
	ds_read_b128 v[236:239], v200 offset:6144
	ds_read_b128 v[240:243], v200 offset:7168
	s_waitcnt vmcnt(8)
	s_waitcnt lgkmcnt(0)
	s_barrier
	s_waitcnt lgkmcnt(0)
	v_mfma_f32_16x16x32_bf16 v[126:129], v[130:133], v[210:213], v[126:129]
	v_mfma_f32_16x16x32_bf16 v[122:125], v[138:141], v[210:213], v[122:125]
	v_mfma_f32_16x16x32_bf16 v[110:113], v[130:133], v[220:223], v[110:113]
	v_mfma_f32_16x16x32_bf16 v[106:109], v[138:141], v[220:223], v[106:109]
	v_mfma_f32_16x16x32_bf16 v[94:97], v[130:133], v[228:231], v[94:97]
	v_mfma_f32_16x16x32_bf16 v[90:93], v[138:141], v[228:231], v[90:93]
	v_mfma_f32_16x16x32_bf16 v[78:81], v[130:133], v[236:239], v[78:81]
	v_mfma_f32_16x16x32_bf16 v[74:77], v[138:141], v[236:239], v[74:77]
	v_mfma_f32_16x16x32_bf16 v[126:129], v[134:137], v[216:219], v[126:129]
	v_mfma_f32_16x16x32_bf16 v[122:125], v[142:145], v[216:219], v[122:125]
	v_mfma_f32_16x16x32_bf16 v[110:113], v[134:137], v[224:227], v[110:113]
	v_mfma_f32_16x16x32_bf16 v[106:109], v[142:145], v[224:227], v[106:109]
	v_mfma_f32_16x16x32_bf16 v[94:97], v[134:137], v[232:235], v[94:97]
	v_mfma_f32_16x16x32_bf16 v[90:93], v[142:145], v[232:235], v[90:93]
	v_mfma_f32_16x16x32_bf16 v[78:81], v[134:137], v[240:243], v[78:81]
	v_mfma_f32_16x16x32_bf16 v[74:77], v[142:145], v[240:243], v[74:77]
	v_mfma_f32_16x16x32_bf16 v[118:121], v[170:173], v[210:213], v[118:121]
	v_mfma_f32_16x16x32_bf16 v[114:117], v[202:205], v[210:213], v[114:117]
	v_mfma_f32_16x16x32_bf16 v[102:105], v[170:173], v[220:223], v[102:105]
	v_mfma_f32_16x16x32_bf16 v[98:101], v[202:205], v[220:223], v[98:101]
	v_mfma_f32_16x16x32_bf16 v[86:89], v[170:173], v[228:231], v[86:89]
	v_mfma_f32_16x16x32_bf16 v[82:85], v[202:205], v[228:231], v[82:85]
	v_mfma_f32_16x16x32_bf16 v[70:73], v[170:173], v[236:239], v[70:73]
	v_mfma_f32_16x16x32_bf16 v[66:69], v[202:205], v[236:239], v[66:69]
	v_mfma_f32_16x16x32_bf16 v[118:121], v[174:177], v[216:219], v[118:121]
	v_mfma_f32_16x16x32_bf16 v[114:117], v[206:209], v[216:219], v[114:117]
	v_mfma_f32_16x16x32_bf16 v[102:105], v[174:177], v[224:227], v[102:105]
	v_mfma_f32_16x16x32_bf16 v[98:101], v[206:209], v[224:227], v[98:101]
	v_mfma_f32_16x16x32_bf16 v[86:89], v[174:177], v[232:235], v[86:89]
	v_mfma_f32_16x16x32_bf16 v[82:85], v[206:209], v[232:235], v[82:85]
	v_mfma_f32_16x16x32_bf16 v[70:73], v[174:177], v[240:243], v[70:73]
	v_mfma_f32_16x16x32_bf16 v[66:69], v[206:209], v[240:243], v[66:69]
	s_barrier
	s_add_i32 s30, s30, s61
	s_mov_b32 m0, s30
	s_nop 0
	global_load_lds_dwordx4 v154, s[10:11]
	s_add_i32 m0, s30, 0x2000
	s_add_u32 s42, s10, 0x40000
	s_addc_u32 s43, s11, 0
	s_add_i32 s30, s31, s61
	global_load_lds_dwordx4 v158, s[10:11]
	s_mov_b32 m0, s30
	s_nop 0
	global_load_lds_dwordx4 v154, s[42:43]
	s_mov_b32 m0, s59
	s_nop 0
	global_load_lds_dwordx4 v152, s[12:13]
	s_mov_b32 m0, s62
	s_nop 0
	global_load_lds_dwordx4 v156, s[12:13]
	ds_read_b128 v[210:213], v200 offset:16384
	ds_read_b128 v[216:219], v200 offset:17408
	ds_read_b128 v[220:223], v200 offset:18432
	ds_read_b128 v[224:227], v200 offset:19456
	ds_read_b128 v[228:231], v200 offset:20480
	ds_read_b128 v[232:235], v200 offset:21504
	ds_read_b128 v[236:239], v200 offset:22528
	ds_read_b128 v[240:243], v200 offset:23552
	s_waitcnt vmcnt(7)
	s_waitcnt lgkmcnt(0)
	s_barrier
	s_waitcnt lgkmcnt(0)
	v_mfma_f32_16x16x32_bf16 v[62:65], v[130:133], v[210:213], v[62:65]
	v_mfma_f32_16x16x32_bf16 v[58:61], v[138:141], v[210:213], v[58:61]
	v_mfma_f32_16x16x32_bf16 v[46:49], v[130:133], v[220:223], v[46:49]
	v_mfma_f32_16x16x32_bf16 v[42:45], v[138:141], v[220:223], v[42:45]
	v_mfma_f32_16x16x32_bf16 v[30:33], v[130:133], v[228:231], v[30:33]
	v_mfma_f32_16x16x32_bf16 v[26:29], v[138:141], v[228:231], v[26:29]
	v_mfma_f32_16x16x32_bf16 v[14:17], v[130:133], v[236:239], v[14:17]
	v_mfma_f32_16x16x32_bf16 v[10:13], v[138:141], v[236:239], v[10:13]
	v_mfma_f32_16x16x32_bf16 v[62:65], v[134:137], v[216:219], v[62:65]
	v_mfma_f32_16x16x32_bf16 v[58:61], v[142:145], v[216:219], v[58:61]
	v_mfma_f32_16x16x32_bf16 v[46:49], v[134:137], v[224:227], v[46:49]
	v_mfma_f32_16x16x32_bf16 v[42:45], v[142:145], v[224:227], v[42:45]
	v_mfma_f32_16x16x32_bf16 v[30:33], v[134:137], v[232:235], v[30:33]
	v_mfma_f32_16x16x32_bf16 v[26:29], v[142:145], v[232:235], v[26:29]
	v_mfma_f32_16x16x32_bf16 v[14:17], v[134:137], v[240:243], v[14:17]
	v_mfma_f32_16x16x32_bf16 v[10:13], v[142:145], v[240:243], v[10:13]
	v_mfma_f32_16x16x32_bf16 v[54:57], v[170:173], v[210:213], v[54:57]
	v_mfma_f32_16x16x32_bf16 v[50:53], v[202:205], v[210:213], v[50:53]
	v_mfma_f32_16x16x32_bf16 v[38:41], v[170:173], v[220:223], v[38:41]
	v_mfma_f32_16x16x32_bf16 v[34:37], v[202:205], v[220:223], v[34:37]
	v_mfma_f32_16x16x32_bf16 v[22:25], v[170:173], v[228:231], v[22:25]
	v_mfma_f32_16x16x32_bf16 v[18:21], v[202:205], v[228:231], v[18:21]
	v_mfma_f32_16x16x32_bf16 v[6:9], v[170:173], v[236:239], v[6:9]
	v_mfma_f32_16x16x32_bf16 v[2:5], v[202:205], v[236:239], v[2:5]
	v_mfma_f32_16x16x32_bf16 v[54:57], v[174:177], v[216:219], v[54:57]
	v_mfma_f32_16x16x32_bf16 v[50:53], v[206:209], v[216:219], v[50:53]
	v_mfma_f32_16x16x32_bf16 v[38:41], v[174:177], v[224:227], v[38:41]
	v_mfma_f32_16x16x32_bf16 v[34:37], v[206:209], v[224:227], v[34:37]
	v_mfma_f32_16x16x32_bf16 v[22:25], v[174:177], v[232:235], v[22:25]
	v_mfma_f32_16x16x32_bf16 v[18:21], v[206:209], v[232:235], v[18:21]
	v_mfma_f32_16x16x32_bf16 v[6:9], v[174:177], v[240:243], v[6:9]
	v_mfma_f32_16x16x32_bf16 v[2:5], v[206:209], v[240:243], v[2:5]
	s_barrier
	s_add_i32 m0, s30, 0x2000
	s_nop 0
	global_load_lds_dwordx4 v158, s[42:43]
	s_add_i32 s30, 0, 0x18000
	s_add_i32 s31, 0, 0x1c000
	ds_read_b128 v[130:133], v244 offset:32768
	ds_read_b128 v[134:137], v244 offset:33792
	ds_read_b128 v[138:141], v244 offset:34816
	ds_read_b128 v[142:145], v244 offset:35840
	ds_read_b128 v[170:173], v244 offset:49152
	ds_read_b128 v[174:177], v244 offset:50176
	ds_read_b128 v[202:205], v244 offset:51200
	ds_read_b128 v[206:209], v244 offset:52224
	s_add_u32 s12, s12, 0x40000
	s_addc_u32 s13, s13, 0
	s_mov_b32 m0, s63
	ds_read_b128 v[210:213], v200 offset:32768
	ds_read_b128 v[216:219], v200 offset:33792
	ds_read_b128 v[220:223], v200 offset:34816
	ds_read_b128 v[224:227], v200 offset:35840
	ds_read_b128 v[228:231], v200 offset:36864
	ds_read_b128 v[232:235], v200 offset:37888
	ds_read_b128 v[236:239], v200 offset:38912
	ds_read_b128 v[240:243], v200 offset:39936
	global_load_lds_dwordx4 v152, s[12:13]
	s_mov_b32 m0, s64
	s_nop 0
	global_load_lds_dwordx4 v156, s[12:13]
	s_waitcnt vmcnt(8)
	s_waitcnt lgkmcnt(0)
	s_barrier
	s_waitcnt lgkmcnt(0)
	v_mfma_f32_16x16x32_bf16 v[126:129], v[130:133], v[210:213], v[126:129]
	v_mfma_f32_16x16x32_bf16 v[122:125], v[138:141], v[210:213], v[122:125]
	v_mfma_f32_16x16x32_bf16 v[110:113], v[130:133], v[220:223], v[110:113]
	v_mfma_f32_16x16x32_bf16 v[106:109], v[138:141], v[220:223], v[106:109]
	v_mfma_f32_16x16x32_bf16 v[94:97], v[130:133], v[228:231], v[94:97]
	v_mfma_f32_16x16x32_bf16 v[90:93], v[138:141], v[228:231], v[90:93]
	v_mfma_f32_16x16x32_bf16 v[78:81], v[130:133], v[236:239], v[78:81]
	v_mfma_f32_16x16x32_bf16 v[74:77], v[138:141], v[236:239], v[74:77]
	v_mfma_f32_16x16x32_bf16 v[126:129], v[134:137], v[216:219], v[126:129]
	v_mfma_f32_16x16x32_bf16 v[122:125], v[142:145], v[216:219], v[122:125]
	v_mfma_f32_16x16x32_bf16 v[110:113], v[134:137], v[224:227], v[110:113]
	v_mfma_f32_16x16x32_bf16 v[106:109], v[142:145], v[224:227], v[106:109]
	v_mfma_f32_16x16x32_bf16 v[94:97], v[134:137], v[232:235], v[94:97]
	v_mfma_f32_16x16x32_bf16 v[90:93], v[142:145], v[232:235], v[90:93]
	v_mfma_f32_16x16x32_bf16 v[78:81], v[134:137], v[240:243], v[78:81]
	v_mfma_f32_16x16x32_bf16 v[74:77], v[142:145], v[240:243], v[74:77]
	v_mfma_f32_16x16x32_bf16 v[118:121], v[170:173], v[210:213], v[118:121]
	v_mfma_f32_16x16x32_bf16 v[114:117], v[202:205], v[210:213], v[114:117]
	v_mfma_f32_16x16x32_bf16 v[102:105], v[170:173], v[220:223], v[102:105]
	v_mfma_f32_16x16x32_bf16 v[98:101], v[202:205], v[220:223], v[98:101]
	v_mfma_f32_16x16x32_bf16 v[86:89], v[170:173], v[228:231], v[86:89]
	v_mfma_f32_16x16x32_bf16 v[82:85], v[202:205], v[228:231], v[82:85]
	v_mfma_f32_16x16x32_bf16 v[70:73], v[170:173], v[236:239], v[70:73]
	v_mfma_f32_16x16x32_bf16 v[66:69], v[202:205], v[236:239], v[66:69]
	v_mfma_f32_16x16x32_bf16 v[118:121], v[174:177], v[216:219], v[118:121]
	v_mfma_f32_16x16x32_bf16 v[114:117], v[206:209], v[216:219], v[114:117]
	v_mfma_f32_16x16x32_bf16 v[102:105], v[174:177], v[224:227], v[102:105]
	v_mfma_f32_16x16x32_bf16 v[98:101], v[206:209], v[224:227], v[98:101]
	v_mfma_f32_16x16x32_bf16 v[86:89], v[174:177], v[232:235], v[86:89]
	v_mfma_f32_16x16x32_bf16 v[82:85], v[206:209], v[232:235], v[82:85]
	v_mfma_f32_16x16x32_bf16 v[70:73], v[174:177], v[240:243], v[70:73]
	v_mfma_f32_16x16x32_bf16 v[66:69], v[206:209], v[240:243], v[66:69]
	s_barrier
	s_add_i32 m0, s30, s61
	s_add_u32 s42, s10, 0x80
	s_addc_u32 s43, s11, 0
	global_load_lds_dwordx4 v154, s[42:43]
	s_add_i32 m0, m0, 0x2000
	s_add_u32 s10, s10, 0x40080
	s_addc_u32 s11, s11, 0
	global_load_lds_dwordx4 v158, s[42:43]
	s_add_i32 m0, s31, s61
	s_add_u32 s42, s12, 0xfffc0080
	s_addc_u32 s43, s13, -1
	global_load_lds_dwordx4 v154, s[10:11]
	s_add_i32 m0, m0, 0x2000
	s_nop 0
	global_load_lds_dwordx4 v158, s[10:11]
	s_mov_b32 m0, s66
	s_nop 0
	global_load_lds_dwordx4 v152, s[42:43]
	s_mov_b32 m0, s67
	s_add_i32 s12, s31, s61
	global_load_lds_dwordx4 v156, s[42:43]
	ds_read_b128 v[210:213], v200 offset:49152
	ds_read_b128 v[216:219], v200 offset:50176
	ds_read_b128 v[220:223], v200 offset:51200
	ds_read_b128 v[224:227], v200 offset:52224
	ds_read_b128 v[228:231], v200 offset:53248
	ds_read_b128 v[232:235], v200 offset:54272
	ds_read_b128 v[236:239], v200 offset:55296
	ds_read_b128 v[240:243], v200 offset:56320
	s_add_i32 s29, s29, 2
	s_add_u32 s8, s8, 0x100
	s_addc_u32 s9, s9, 0
	s_add_u32 s27, s27, 0x100
	s_addc_u32 s28, s28, 0
	s_cmp_gt_u32 s29, 13
	s_cbranch_scc1 .Lk1_skip
	s_add_u32 s10, s8, 0xfffc0080
	s_addc_u32 s11, s9, -1
	s_add_i32 s30, 0, 0x10000
	s_cmp_eq_u32 s29, 12
	s_cselect_b32 s13, s3, s11
	s_cselect_b32 s12, s24, s10
	s_cselect_b32 s11, s25, s28
	s_cselect_b32 s10, s26, s27
	s_add_i32 s31, 0, 0x14000

.LBB0_640:
	ds_read_b128 v[144:147], v153
	ds_read_b128 v[156:159], v153 offset:1024
	ds_read_b128 v[160:163], v153 offset:2048
	ds_read_b128 v[164:167], v153 offset:3072
	ds_read_b128 v[168:171], v154
	ds_read_b128 v[172:175], v154 offset:1024
	ds_read_b128 v[176:179], v154 offset:2048
	ds_read_b128 v[180:183], v154 offset:3072
	s_add_u32 s28, s12, 0xfffc0080
	s_addc_u32 s29, s13, -1
	s_cmp_eq_u32 s27, 12
	s_cselect_b32 s57, s11, s29
	s_cselect_b32 s56, s14, s28
	s_cselect_b32 s55, s15, s26
	s_cselect_b32 s54, s24, s25
	s_add_i32 m0, s19, 0xc000
	s_nop 0
	global_load_lds_dwordx4 v136, s[12:13]
	s_add_i32 m0, s19, 0xe000
	s_nop 0
	global_load_lds_dwordx4 v138, s[12:13]
	ds_read_b128 v[184:187], v155
	ds_read_b128 v[188:191], v155 offset:1024
	ds_read_b128 v[192:195], v155 offset:2048
	ds_read_b128 v[196:199], v155 offset:3072
	ds_read_b128 v[200:203], v155 offset:4096
	ds_read_b128 v[204:207], v155 offset:5120
	ds_read_b128 v[208:211], v155 offset:6144
	ds_read_b128 v[216:219], v155 offset:7168
	s_waitcnt vmcnt(8)
	s_waitcnt lgkmcnt(0)
	s_barrier
	s_waitcnt lgkmcnt(0)
	v_mfma_f32_16x16x32_bf16 v[124:127], v[144:147], v[184:187], v[124:127]
	v_mfma_f32_16x16x32_bf16 v[120:123], v[160:163], v[184:187], v[120:123]
	v_mfma_f32_16x16x32_bf16 v[108:111], v[144:147], v[192:195], v[108:111]
	v_mfma_f32_16x16x32_bf16 v[104:107], v[160:163], v[192:195], v[104:107]
	v_mfma_f32_16x16x32_bf16 v[92:95], v[144:147], v[200:203], v[92:95]
	v_mfma_f32_16x16x32_bf16 v[88:91], v[160:163], v[200:203], v[88:91]
	v_mfma_f32_16x16x32_bf16 v[76:79], v[144:147], v[208:211], v[76:79]
	v_mfma_f32_16x16x32_bf16 v[72:75], v[160:163], v[208:211], v[72:75]
	v_mfma_f32_16x16x32_bf16 v[124:127], v[156:159], v[188:191], v[124:127]
	v_mfma_f32_16x16x32_bf16 v[120:123], v[164:167], v[188:191], v[120:123]
	v_mfma_f32_16x16x32_bf16 v[108:111], v[156:159], v[196:199], v[108:111]
	v_mfma_f32_16x16x32_bf16 v[104:107], v[164:167], v[196:199], v[104:107]
	v_mfma_f32_16x16x32_bf16 v[92:95], v[156:159], v[204:207], v[92:95]
	v_mfma_f32_16x16x32_bf16 v[88:91], v[164:167], v[204:207], v[88:91]
	v_mfma_f32_16x16x32_bf16 v[76:79], v[156:159], v[216:219], v[76:79]
	v_mfma_f32_16x16x32_bf16 v[72:75], v[164:167], v[216:219], v[72:75]
	v_mfma_f32_16x16x32_bf16 v[116:119], v[168:171], v[184:187], v[116:119]
	v_mfma_f32_16x16x32_bf16 v[112:115], v[176:179], v[184:187], v[112:115]
	v_mfma_f32_16x16x32_bf16 v[100:103], v[168:171], v[192:195], v[100:103]
	v_mfma_f32_16x16x32_bf16 v[96:99], v[176:179], v[192:195], v[96:99]
	v_mfma_f32_16x16x32_bf16 v[84:87], v[168:171], v[200:203], v[84:87]
	v_mfma_f32_16x16x32_bf16 v[80:83], v[176:179], v[200:203], v[80:83]
	v_mfma_f32_16x16x32_bf16 v[68:71], v[168:171], v[208:211], v[68:71]
	v_mfma_f32_16x16x32_bf16 v[64:67], v[176:179], v[208:211], v[64:67]
	v_mfma_f32_16x16x32_bf16 v[116:119], v[172:175], v[188:191], v[116:119]
	v_mfma_f32_16x16x32_bf16 v[112:115], v[180:183], v[188:191], v[112:115]
	v_mfma_f32_16x16x32_bf16 v[100:103], v[172:175], v[196:199], v[100:103]
	v_mfma_f32_16x16x32_bf16 v[96:99], v[180:183], v[196:199], v[96:99]
	v_mfma_f32_16x16x32_bf16 v[84:87], v[172:175], v[204:207], v[84:87]
	v_mfma_f32_16x16x32_bf16 v[80:83], v[180:183], v[204:207], v[80:83]
	v_mfma_f32_16x16x32_bf16 v[68:71], v[172:175], v[216:219], v[68:71]
	v_mfma_f32_16x16x32_bf16 v[64:67], v[180:183], v[216:219], v[64:67]
	s_barrier
	s_add_i32 s28, s63, s18
	s_mov_b32 m0, s28
	s_nop 0
	global_load_lds_dwordx4 v130, s[54:55]
	s_add_i32 m0, s28, 0x2000
	s_add_u32 s28, s54, 0x40000
	s_addc_u32 s29, s55, 0
	s_add_i32 s30, s64, s18
	global_load_lds_dwordx4 v134, s[54:55]
	s_mov_b32 m0, s30
	s_nop 0
	global_load_lds_dwordx4 v130, s[28:29]
	s_add_i32 m0, s30, 0x2000
	s_nop 0
	global_load_lds_dwordx4 v134, s[28:29]
	s_mov_b32 m0, s19
	s_nop 0
	global_load_lds_dwordx4 v128, s[56:57]
	s_mov_b32 m0, s20
	s_nop 0
	global_load_lds_dwordx4 v132, s[56:57]
	ds_read_b128 v[184:187], v155 offset:16384
	ds_read_b128 v[188:191], v155 offset:17408
	ds_read_b128 v[192:195], v155 offset:18432
	ds_read_b128 v[196:199], v155 offset:19456
	ds_read_b128 v[200:203], v155 offset:20480
	ds_read_b128 v[204:207], v155 offset:21504
	ds_read_b128 v[208:211], v155 offset:22528
	ds_read_b128 v[216:219], v155 offset:23552
	s_waitcnt vmcnt(8)
	s_waitcnt lgkmcnt(0)
	s_barrier
	s_waitcnt lgkmcnt(0)
	v_mfma_f32_16x16x32_bf16 v[60:63], v[144:147], v[184:187], v[60:63]
	v_mfma_f32_16x16x32_bf16 v[56:59], v[160:163], v[184:187], v[56:59]
	v_mfma_f32_16x16x32_bf16 v[44:47], v[144:147], v[192:195], v[44:47]
	v_mfma_f32_16x16x32_bf16 v[40:43], v[160:163], v[192:195], v[40:43]
	v_mfma_f32_16x16x32_bf16 v[28:31], v[144:147], v[200:203], v[28:31]
	v_mfma_f32_16x16x32_bf16 v[24:27], v[160:163], v[200:203], v[24:27]
	v_mfma_f32_16x16x32_bf16 v[12:15], v[144:147], v[208:211], v[12:15]
	v_mfma_f32_16x16x32_bf16 v[8:11], v[160:163], v[208:211], v[8:11]
	v_mfma_f32_16x16x32_bf16 v[60:63], v[156:159], v[188:191], v[60:63]
	v_mfma_f32_16x16x32_bf16 v[56:59], v[164:167], v[188:191], v[56:59]
	v_mfma_f32_16x16x32_bf16 v[44:47], v[156:159], v[196:199], v[44:47]
	v_mfma_f32_16x16x32_bf16 v[40:43], v[164:167], v[196:199], v[40:43]
	v_mfma_f32_16x16x32_bf16 v[28:31], v[156:159], v[204:207], v[28:31]
	v_mfma_f32_16x16x32_bf16 v[24:27], v[164:167], v[204:207], v[24:27]
	v_mfma_f32_16x16x32_bf16 v[12:15], v[156:159], v[216:219], v[12:15]
	v_mfma_f32_16x16x32_bf16 v[8:11], v[164:167], v[216:219], v[8:11]
	v_mfma_f32_16x16x32_bf16 v[52:55], v[168:171], v[184:187], v[52:55]
	v_mfma_f32_16x16x32_bf16 v[48:51], v[176:179], v[184:187], v[48:51]
	v_mfma_f32_16x16x32_bf16 v[36:39], v[168:171], v[192:195], v[36:39]
	v_mfma_f32_16x16x32_bf16 v[32:35], v[176:179], v[192:195], v[32:35]
	v_mfma_f32_16x16x32_bf16 v[20:23], v[168:171], v[200:203], v[20:23]
	v_mfma_f32_16x16x32_bf16 v[16:19], v[176:179], v[200:203], v[16:19]
	v_mfma_f32_16x16x32_bf16 v[4:7], v[168:171], v[208:211], v[4:7]
	v_mfma_f32_16x16x32_bf16 v[0:3], v[176:179], v[208:211], v[0:3]
	v_mfma_f32_16x16x32_bf16 v[52:55], v[172:175], v[188:191], v[52:55]
	v_mfma_f32_16x16x32_bf16 v[48:51], v[180:183], v[188:191], v[48:51]
	v_mfma_f32_16x16x32_bf16 v[36:39], v[172:175], v[196:199], v[36:39]
	v_mfma_f32_16x16x32_bf16 v[32:35], v[180:183], v[196:199], v[32:35]
	v_mfma_f32_16x16x32_bf16 v[20:23], v[172:175], v[204:207], v[20:23]
	v_mfma_f32_16x16x32_bf16 v[16:19], v[180:183], v[204:207], v[16:19]
	v_mfma_f32_16x16x32_bf16 v[4:7], v[172:175], v[216:219], v[4:7]
	v_mfma_f32_16x16x32_bf16 v[0:3], v[180:183], v[216:219], v[0:3]
	s_barrier
	s_add_i32 s30, 0, 0x18000
	s_add_i32 s31, 0, 0x1c000
	ds_read_b128 v[144:147], v153 offset:32768
	ds_read_b128 v[156:159], v153 offset:33792
	ds_read_b128 v[160:163], v153 offset:34816
	ds_read_b128 v[164:167], v153 offset:35840
	ds_read_b128 v[168:171], v153 offset:49152
	ds_read_b128 v[172:175], v153 offset:50176
	ds_read_b128 v[176:179], v153 offset:51200
	ds_read_b128 v[180:183], v153 offset:52224
	s_add_u32 s28, s56, 0x40000
	s_addc_u32 s29, s57, 0
	s_mov_b32 m0, s21
	s_nop 0
	global_load_lds_dwordx4 v128, s[28:29]
	s_mov_b32 m0, s22
	s_nop 0
	global_load_lds_dwordx4 v132, s[28:29]
	ds_read_b128 v[184:187], v155 offset:32768
	ds_read_b128 v[188:191], v155 offset:33792
	ds_read_b128 v[192:195], v155 offset:34816
	ds_read_b128 v[196:199], v155 offset:35840
	ds_read_b128 v[200:203], v155 offset:36864
	ds_read_b128 v[204:207], v155 offset:37888
	ds_read_b128 v[208:211], v155 offset:38912
	ds_read_b128 v[216:219], v155 offset:39936
	s_waitcnt vmcnt(8)
	s_waitcnt lgkmcnt(0)
	s_barrier
	s_waitcnt lgkmcnt(0)
	v_mfma_f32_16x16x32_bf16 v[124:127], v[144:147], v[184:187], v[124:127]
	v_mfma_f32_16x16x32_bf16 v[120:123], v[160:163], v[184:187], v[120:123]
	v_mfma_f32_16x16x32_bf16 v[108:111], v[144:147], v[192:195], v[108:111]
	v_mfma_f32_16x16x32_bf16 v[104:107], v[160:163], v[192:195], v[104:107]
	v_mfma_f32_16x16x32_bf16 v[92:95], v[144:147], v[200:203], v[92:95]
	v_mfma_f32_16x16x32_bf16 v[88:91], v[160:163], v[200:203], v[88:91]
	v_mfma_f32_16x16x32_bf16 v[76:79], v[144:147], v[208:211], v[76:79]
	v_mfma_f32_16x16x32_bf16 v[72:75], v[160:163], v[208:211], v[72:75]
	v_mfma_f32_16x16x32_bf16 v[124:127], v[156:159], v[188:191], v[124:127]
	v_mfma_f32_16x16x32_bf16 v[120:123], v[164:167], v[188:191], v[120:123]
	v_mfma_f32_16x16x32_bf16 v[108:111], v[156:159], v[196:199], v[108:111]
	v_mfma_f32_16x16x32_bf16 v[104:107], v[164:167], v[196:199], v[104:107]
	v_mfma_f32_16x16x32_bf16 v[92:95], v[156:159], v[204:207], v[92:95]
	v_mfma_f32_16x16x32_bf16 v[88:91], v[164:167], v[204:207], v[88:91]
	v_mfma_f32_16x16x32_bf16 v[76:79], v[156:159], v[216:219], v[76:79]
	v_mfma_f32_16x16x32_bf16 v[72:75], v[164:167], v[216:219], v[72:75]
	v_mfma_f32_16x16x32_bf16 v[116:119], v[168:171], v[184:187], v[116:119]
	v_mfma_f32_16x16x32_bf16 v[112:115], v[176:179], v[184:187], v[112:115]
	v_mfma_f32_16x16x32_bf16 v[100:103], v[168:171], v[192:195], v[100:103]
	v_mfma_f32_16x16x32_bf16 v[96:99], v[176:179], v[192:195], v[96:99]
	v_mfma_f32_16x16x32_bf16 v[84:87], v[168:171], v[200:203], v[84:87]
	v_mfma_f32_16x16x32_bf16 v[80:83], v[176:179], v[200:203], v[80:83]
	v_mfma_f32_16x16x32_bf16 v[68:71], v[168:171], v[208:211], v[68:71]
	v_mfma_f32_16x16x32_bf16 v[64:67], v[176:179], v[208:211], v[64:67]
	v_mfma_f32_16x16x32_bf16 v[116:119], v[172:175], v[188:191], v[116:119]
	v_mfma_f32_16x16x32_bf16 v[112:115], v[180:183], v[188:191], v[112:115]
	v_mfma_f32_16x16x32_bf16 v[100:103], v[172:175], v[196:199], v[100:103]
	v_mfma_f32_16x16x32_bf16 v[96:99], v[180:183], v[196:199], v[96:99]
	v_mfma_f32_16x16x32_bf16 v[84:87], v[172:175], v[204:207], v[84:87]
	v_mfma_f32_16x16x32_bf16 v[80:83], v[180:183], v[204:207], v[80:83]
	v_mfma_f32_16x16x32_bf16 v[68:71], v[172:175], v[216:219], v[68:71]
	v_mfma_f32_16x16x32_bf16 v[64:67], v[180:183], v[216:219], v[64:67]
	s_barrier
	s_add_i32 m0, s30, s18
	s_add_u32 s28, s54, 0x80
	s_addc_u32 s29, s55, 0
	global_load_lds_dwordx4 v130, s[28:29]
	s_add_i32 m0, m0, 0x2000
	s_add_i32 s30, s31, s18
	global_load_lds_dwordx4 v134, s[28:29]
	s_add_u32 s28, s28, 0x40000
	s_addc_u32 s29, s29, 0
	s_mov_b32 m0, s30
	s_nop 0
	global_load_lds_dwordx4 v130, s[28:29]
	s_add_i32 m0, s30, 0x2000
	s_nop 0
	global_load_lds_dwordx4 v134, s[28:29]
	s_add_u32 s28, s56, 0x80
	s_addc_u32 s29, s57, 0
	s_mov_b32 m0, s33
	s_nop 0
	global_load_lds_dwordx4 v128, s[28:29]
	s_mov_b32 m0, s58
	s_nop 0
	global_load_lds_dwordx4 v132, s[28:29]
	ds_read_b128 v[184:187], v155 offset:49152
	ds_read_b128 v[188:191], v155 offset:50176
	ds_read_b128 v[192:195], v155 offset:51200
	ds_read_b128 v[196:199], v155 offset:52224
	ds_read_b128 v[200:203], v155 offset:53248
	ds_read_b128 v[204:207], v155 offset:54272
	ds_read_b128 v[208:211], v155 offset:55296
	ds_read_b128 v[216:219], v155 offset:56320
	s_add_u32 s28, s54, 0x40080
	s_addc_u32 s29, s55, 0
	s_waitcnt vmcnt(8)
	s_waitcnt lgkmcnt(0)
	s_barrier
	s_waitcnt lgkmcnt(0)
	v_mfma_f32_16x16x32_bf16 v[60:63], v[144:147], v[184:187], v[60:63]
	v_mfma_f32_16x16x32_bf16 v[56:59], v[160:163], v[184:187], v[56:59]
	v_mfma_f32_16x16x32_bf16 v[44:47], v[144:147], v[192:195], v[44:47]
	v_mfma_f32_16x16x32_bf16 v[40:43], v[160:163], v[192:195], v[40:43]
	v_mfma_f32_16x16x32_bf16 v[28:31], v[144:147], v[200:203], v[28:31]
	v_mfma_f32_16x16x32_bf16 v[24:27], v[160:163], v[200:203], v[24:27]
	v_mfma_f32_16x16x32_bf16 v[12:15], v[144:147], v[208:211], v[12:15]
	v_mfma_f32_16x16x32_bf16 v[8:11], v[160:163], v[208:211], v[8:11]
	v_mfma_f32_16x16x32_bf16 v[60:63], v[156:159], v[188:191], v[60:63]
	v_mfma_f32_16x16x32_bf16 v[56:59], v[164:167], v[188:191], v[56:59]
	v_mfma_f32_16x16x32_bf16 v[44:47], v[156:159], v[196:199], v[44:47]
	v_mfma_f32_16x16x32_bf16 v[40:43], v[164:167], v[196:199], v[40:43]
	v_mfma_f32_16x16x32_bf16 v[28:31], v[156:159], v[204:207], v[28:31]
	v_mfma_f32_16x16x32_bf16 v[24:27], v[164:167], v[204:207], v[24:27]
	v_mfma_f32_16x16x32_bf16 v[12:15], v[156:159], v[216:219], v[12:15]
	v_mfma_f32_16x16x32_bf16 v[8:11], v[164:167], v[216:219], v[8:11]
	v_mfma_f32_16x16x32_bf16 v[52:55], v[168:171], v[184:187], v[52:55]
	v_mfma_f32_16x16x32_bf16 v[48:51], v[176:179], v[184:187], v[48:51]
	v_mfma_f32_16x16x32_bf16 v[36:39], v[168:171], v[192:195], v[36:39]
	v_mfma_f32_16x16x32_bf16 v[32:35], v[176:179], v[192:195], v[32:35]
	v_mfma_f32_16x16x32_bf16 v[20:23], v[168:171], v[200:203], v[20:23]
	v_mfma_f32_16x16x32_bf16 v[16:19], v[176:179], v[200:203], v[16:19]
	v_mfma_f32_16x16x32_bf16 v[4:7], v[168:171], v[208:211], v[4:7]
	v_mfma_f32_16x16x32_bf16 v[0:3], v[176:179], v[208:211], v[0:3]
	v_mfma_f32_16x16x32_bf16 v[52:55], v[172:175], v[188:191], v[52:55]
	v_mfma_f32_16x16x32_bf16 v[48:51], v[180:183], v[188:191], v[48:51]
	v_mfma_f32_16x16x32_bf16 v[36:39], v[172:175], v[196:199], v[36:39]
	v_mfma_f32_16x16x32_bf16 v[32:35], v[180:183], v[196:199], v[32:35]
	v_mfma_f32_16x16x32_bf16 v[20:23], v[172:175], v[204:207], v[20:23]
	v_mfma_f32_16x16x32_bf16 v[16:19], v[180:183], v[204:207], v[16:19]
	v_mfma_f32_16x16x32_bf16 v[4:7], v[172:175], v[216:219], v[4:7]
	v_mfma_f32_16x16x32_bf16 v[0:3], v[180:183], v[216:219], v[0:3]
	s_barrier
	s_add_i32 s27, s27, 2
	s_add_u32 s12, s12, 0x100
	s_addc_u32 s13, s13, 0
	s_add_u32 s25, s25, 0x100
	s_addc_u32 s26, s26, 0
	s_cmp_gt_u32 s27, 13
	s_cbranch_scc0 .LBB0_640
	s_setprio 0
	s_and_b64 vcc, exec, s[8:9]
	s_cbranch_vccz .LBB0_643
	s_barrier

.LBB0_744:
	ds_read_b128 v[80:83], v226
	ds_read_b128 v[84:87], v226 offset:1024
	ds_read_b128 v[88:91], v226 offset:2048
	ds_read_b128 v[92:95], v226 offset:3072
	ds_read_b128 v[128:131], v227
	ds_read_b128 v[132:135], v227 offset:1024
	ds_read_b128 v[152:155], v227 offset:2048
	ds_read_b128 v[156:159], v227 offset:3072
	s_add_u32 s26, s46, 0xfffc0080
	s_addc_u32 s27, s47, -1
	s_cmp_eq_u32 s25, 12
	s_cselect_b32 s89, s11, s27
	s_cselect_b32 s88, s14, s26
	s_cselect_b32 s49, s15, s24
	s_cselect_b32 s48, s16, s17
	s_add_i32 m0, s13, 0xc000
	s_nop 0
	global_load_lds_dwordx4 v184, s[46:47]
	s_add_i32 m0, s13, 0xe000
	s_nop 0
	global_load_lds_dwordx4 v186, s[46:47]
	ds_read_b128 v[160:163], v228
	ds_read_b128 v[164:167], v228 offset:1024
	ds_read_b128 v[168:171], v228 offset:2048
	ds_read_b128 v[172:175], v228 offset:3072
	ds_read_b128 v[192:195], v228 offset:4096
	ds_read_b128 v[196:199], v228 offset:5120
	ds_read_b128 v[200:203], v228 offset:6144
	ds_read_b128 v[204:207], v228 offset:7168
	s_waitcnt vmcnt(8)
	s_waitcnt lgkmcnt(0)
	s_barrier
	s_waitcnt lgkmcnt(0)
	v_mfma_f32_16x16x32_bf16 v[76:79], v[80:83], v[160:163], v[76:79]
	v_mfma_f32_16x16x32_bf16 v[64:67], v[88:91], v[160:163], v[64:67]
	v_mfma_f32_16x16x32_bf16 v[148:151], v[80:83], v[168:171], v[148:151]
	v_mfma_f32_16x16x32_bf16 v[140:143], v[88:91], v[168:171], v[140:143]
	v_mfma_f32_16x16x32_bf16 v[124:127], v[80:83], v[192:195], v[124:127]
	v_mfma_f32_16x16x32_bf16 v[120:123], v[88:91], v[192:195], v[120:123]
	v_mfma_f32_16x16x32_bf16 v[72:75], v[80:83], v[200:203], v[72:75]
	v_mfma_f32_16x16x32_bf16 v[60:63], v[88:91], v[200:203], v[60:63]
	v_mfma_f32_16x16x32_bf16 v[76:79], v[84:87], v[164:167], v[76:79]
	v_mfma_f32_16x16x32_bf16 v[64:67], v[92:95], v[164:167], v[64:67]
	v_mfma_f32_16x16x32_bf16 v[148:151], v[84:87], v[172:175], v[148:151]
	v_mfma_f32_16x16x32_bf16 v[140:143], v[92:95], v[172:175], v[140:143]
	v_mfma_f32_16x16x32_bf16 v[124:127], v[84:87], v[196:199], v[124:127]
	v_mfma_f32_16x16x32_bf16 v[120:123], v[92:95], v[196:199], v[120:123]
	v_mfma_f32_16x16x32_bf16 v[72:75], v[84:87], v[204:207], v[72:75]
	v_mfma_f32_16x16x32_bf16 v[60:63], v[92:95], v[204:207], v[60:63]
	v_mfma_f32_16x16x32_bf16 v[144:147], v[128:131], v[160:163], v[144:147]
	v_mfma_f32_16x16x32_bf16 v[136:139], v[152:155], v[160:163], v[136:139]
	v_mfma_f32_16x16x32_bf16 v[116:119], v[128:131], v[168:171], v[116:119]
	v_mfma_f32_16x16x32_bf16 v[112:115], v[152:155], v[168:171], v[112:115]
	v_mfma_f32_16x16x32_bf16 v[108:111], v[128:131], v[192:195], v[108:111]
	v_mfma_f32_16x16x32_bf16 v[104:107], v[152:155], v[192:195], v[104:107]
	v_mfma_f32_16x16x32_bf16 v[100:103], v[128:131], v[200:203], v[100:103]
	v_mfma_f32_16x16x32_bf16 v[96:99], v[152:155], v[200:203], v[96:99]
	v_mfma_f32_16x16x32_bf16 v[144:147], v[132:135], v[164:167], v[144:147]
	v_mfma_f32_16x16x32_bf16 v[136:139], v[156:159], v[164:167], v[136:139]
	v_mfma_f32_16x16x32_bf16 v[116:119], v[132:135], v[172:175], v[116:119]
	v_mfma_f32_16x16x32_bf16 v[112:115], v[156:159], v[172:175], v[112:115]
	v_mfma_f32_16x16x32_bf16 v[108:111], v[132:135], v[196:199], v[108:111]
	v_mfma_f32_16x16x32_bf16 v[104:107], v[156:159], v[196:199], v[104:107]
	v_mfma_f32_16x16x32_bf16 v[100:103], v[132:135], v[204:207], v[100:103]
	v_mfma_f32_16x16x32_bf16 v[96:99], v[156:159], v[204:207], v[96:99]
	s_barrier
	s_add_i32 s26, s3, s20
	s_mov_b32 m0, s26
	s_nop 0
	global_load_lds_dwordx4 v178, s[48:49]
	s_add_i32 m0, s26, 0x2000
	s_add_u32 s26, s48, 0x40000
	s_addc_u32 s27, s49, 0
	s_add_i32 s28, s93, s20
	global_load_lds_dwordx4 v182, s[48:49]
	s_mov_b32 m0, s28
	s_nop 0
	global_load_lds_dwordx4 v178, s[26:27]
	s_add_i32 m0, s28, 0x2000
	s_nop 0
	global_load_lds_dwordx4 v182, s[26:27]
	s_mov_b32 m0, s13
	s_nop 0
	global_load_lds_dwordx4 v176, s[88:89]
	s_mov_b32 m0, s21
	s_nop 0
	global_load_lds_dwordx4 v180, s[88:89]
	ds_read_b128 v[160:163], v228 offset:16384
	ds_read_b128 v[164:167], v228 offset:17408
	ds_read_b128 v[168:171], v228 offset:18432
	ds_read_b128 v[172:175], v228 offset:19456
	ds_read_b128 v[192:195], v228 offset:20480
	ds_read_b128 v[196:199], v228 offset:21504
	ds_read_b128 v[200:203], v228 offset:22528
	ds_read_b128 v[204:207], v228 offset:23552
	s_waitcnt vmcnt(8)
	s_waitcnt lgkmcnt(0)
	s_barrier
	s_waitcnt lgkmcnt(0)
	v_mfma_f32_16x16x32_bf16 v[68:71], v[80:83], v[160:163], v[68:71]
	v_mfma_f32_16x16x32_bf16 v[36:39], v[88:91], v[160:163], v[36:39]
	v_mfma_f32_16x16x32_bf16 v[52:55], v[80:83], v[168:171], v[52:55]
	v_mfma_f32_16x16x32_bf16 v[44:47], v[88:91], v[168:171], v[44:47]
	v_mfma_f32_16x16x32_bf16 v[28:31], v[80:83], v[192:195], v[28:31]
	v_mfma_f32_16x16x32_bf16 v[24:27], v[88:91], v[192:195], v[24:27]
	v_mfma_f32_16x16x32_bf16 v[56:59], v[80:83], v[200:203], v[56:59]
	v_mfma_f32_16x16x32_bf16 v[32:35], v[88:91], v[200:203], v[32:35]
	v_mfma_f32_16x16x32_bf16 v[68:71], v[84:87], v[164:167], v[68:71]
	v_mfma_f32_16x16x32_bf16 v[36:39], v[92:95], v[164:167], v[36:39]
	v_mfma_f32_16x16x32_bf16 v[52:55], v[84:87], v[172:175], v[52:55]
	v_mfma_f32_16x16x32_bf16 v[44:47], v[92:95], v[172:175], v[44:47]
	v_mfma_f32_16x16x32_bf16 v[28:31], v[84:87], v[196:199], v[28:31]
	v_mfma_f32_16x16x32_bf16 v[24:27], v[92:95], v[196:199], v[24:27]
	v_mfma_f32_16x16x32_bf16 v[56:59], v[84:87], v[204:207], v[56:59]
	v_mfma_f32_16x16x32_bf16 v[32:35], v[92:95], v[204:207], v[32:35]
	v_mfma_f32_16x16x32_bf16 v[48:51], v[128:131], v[160:163], v[48:51]
	v_mfma_f32_16x16x32_bf16 v[40:43], v[152:155], v[160:163], v[40:43]
	v_mfma_f32_16x16x32_bf16 v[20:23], v[128:131], v[168:171], v[20:23]
	v_mfma_f32_16x16x32_bf16 v[16:19], v[152:155], v[168:171], v[16:19]
	v_mfma_f32_16x16x32_bf16 v[12:15], v[128:131], v[192:195], v[12:15]
	v_mfma_f32_16x16x32_bf16 v[8:11], v[152:155], v[192:195], v[8:11]
	v_mfma_f32_16x16x32_bf16 v[4:7], v[128:131], v[200:203], v[4:7]
	v_mfma_f32_16x16x32_bf16 v[0:3], v[152:155], v[200:203], v[0:3]
	v_mfma_f32_16x16x32_bf16 v[48:51], v[132:135], v[164:167], v[48:51]
	v_mfma_f32_16x16x32_bf16 v[40:43], v[156:159], v[164:167], v[40:43]
	v_mfma_f32_16x16x32_bf16 v[20:23], v[132:135], v[172:175], v[20:23]
	v_mfma_f32_16x16x32_bf16 v[16:19], v[156:159], v[172:175], v[16:19]
	v_mfma_f32_16x16x32_bf16 v[12:15], v[132:135], v[196:199], v[12:15]
	v_mfma_f32_16x16x32_bf16 v[8:11], v[156:159], v[196:199], v[8:11]
	v_mfma_f32_16x16x32_bf16 v[4:7], v[132:135], v[204:207], v[4:7]
	v_mfma_f32_16x16x32_bf16 v[0:3], v[156:159], v[204:207], v[0:3]
	s_barrier
	s_add_i32 s28, 0, 0x18000
	s_add_i32 s29, 0, 0x1c000
	ds_read_b128 v[80:83], v226 offset:32768
	ds_read_b128 v[84:87], v226 offset:33792
	ds_read_b128 v[88:91], v226 offset:34816
	ds_read_b128 v[92:95], v226 offset:35840
	ds_read_b128 v[128:131], v226 offset:49152
	ds_read_b128 v[132:135], v226 offset:50176
	ds_read_b128 v[152:155], v226 offset:51200
	ds_read_b128 v[156:159], v226 offset:52224
	s_add_u32 s26, s88, 0x40000
	s_addc_u32 s27, s89, 0
	s_mov_b32 m0, s22
	s_nop 0
	global_load_lds_dwordx4 v176, s[26:27]
	s_mov_b32 m0, s23
	s_nop 0
	global_load_lds_dwordx4 v180, s[26:27]
	ds_read_b128 v[160:163], v228 offset:32768
	ds_read_b128 v[164:167], v228 offset:33792
	ds_read_b128 v[168:171], v228 offset:34816
	ds_read_b128 v[172:175], v228 offset:35840
	ds_read_b128 v[192:195], v228 offset:36864
	ds_read_b128 v[196:199], v228 offset:37888
	ds_read_b128 v[200:203], v228 offset:38912
	ds_read_b128 v[204:207], v228 offset:39936
	s_waitcnt vmcnt(8)
	s_waitcnt lgkmcnt(0)
	s_barrier
	s_waitcnt lgkmcnt(0)
	v_mfma_f32_16x16x32_bf16 v[76:79], v[80:83], v[160:163], v[76:79]
	v_mfma_f32_16x16x32_bf16 v[64:67], v[88:91], v[160:163], v[64:67]
	v_mfma_f32_16x16x32_bf16 v[148:151], v[80:83], v[168:171], v[148:151]
	v_mfma_f32_16x16x32_bf16 v[140:143], v[88:91], v[168:171], v[140:143]
	v_mfma_f32_16x16x32_bf16 v[124:127], v[80:83], v[192:195], v[124:127]
	v_mfma_f32_16x16x32_bf16 v[120:123], v[88:91], v[192:195], v[120:123]
	v_mfma_f32_16x16x32_bf16 v[72:75], v[80:83], v[200:203], v[72:75]
	v_mfma_f32_16x16x32_bf16 v[60:63], v[88:91], v[200:203], v[60:63]
	v_mfma_f32_16x16x32_bf16 v[76:79], v[84:87], v[164:167], v[76:79]
	v_mfma_f32_16x16x32_bf16 v[64:67], v[92:95], v[164:167], v[64:67]
	v_mfma_f32_16x16x32_bf16 v[148:151], v[84:87], v[172:175], v[148:151]
	v_mfma_f32_16x16x32_bf16 v[140:143], v[92:95], v[172:175], v[140:143]
	v_mfma_f32_16x16x32_bf16 v[124:127], v[84:87], v[196:199], v[124:127]
	v_mfma_f32_16x16x32_bf16 v[120:123], v[92:95], v[196:199], v[120:123]
	v_mfma_f32_16x16x32_bf16 v[72:75], v[84:87], v[204:207], v[72:75]
	v_mfma_f32_16x16x32_bf16 v[60:63], v[92:95], v[204:207], v[60:63]
	v_mfma_f32_16x16x32_bf16 v[144:147], v[128:131], v[160:163], v[144:147]
	v_mfma_f32_16x16x32_bf16 v[136:139], v[152:155], v[160:163], v[136:139]
	v_mfma_f32_16x16x32_bf16 v[116:119], v[128:131], v[168:171], v[116:119]
	v_mfma_f32_16x16x32_bf16 v[112:115], v[152:155], v[168:171], v[112:115]
	v_mfma_f32_16x16x32_bf16 v[108:111], v[128:131], v[192:195], v[108:111]
	v_mfma_f32_16x16x32_bf16 v[104:107], v[152:155], v[192:195], v[104:107]
	v_mfma_f32_16x16x32_bf16 v[100:103], v[128:131], v[200:203], v[100:103]
	v_mfma_f32_16x16x32_bf16 v[96:99], v[152:155], v[200:203], v[96:99]
	v_mfma_f32_16x16x32_bf16 v[144:147], v[132:135], v[164:167], v[144:147]
	v_mfma_f32_16x16x32_bf16 v[136:139], v[156:159], v[164:167], v[136:139]
	v_mfma_f32_16x16x32_bf16 v[116:119], v[132:135], v[172:175], v[116:119]
	v_mfma_f32_16x16x32_bf16 v[112:115], v[156:159], v[172:175], v[112:115]
	v_mfma_f32_16x16x32_bf16 v[108:111], v[132:135], v[196:199], v[108:111]
	v_mfma_f32_16x16x32_bf16 v[104:107], v[156:159], v[196:199], v[104:107]
	v_mfma_f32_16x16x32_bf16 v[100:103], v[132:135], v[204:207], v[100:103]
	v_mfma_f32_16x16x32_bf16 v[96:99], v[156:159], v[204:207], v[96:99]
	s_barrier
	s_add_i32 m0, s28, s20
	s_add_u32 s26, s48, 0x80
	s_addc_u32 s27, s49, 0
	global_load_lds_dwordx4 v178, s[26:27]
	s_add_i32 m0, m0, 0x2000
	s_add_i32 s28, s29, s20
	global_load_lds_dwordx4 v182, s[26:27]
	s_add_u32 s26, s26, 0x40000
	s_addc_u32 s27, s27, 0
	s_mov_b32 m0, s28
	s_nop 0
	global_load_lds_dwordx4 v178, s[26:27]
	s_add_i32 m0, s28, 0x2000
	s_nop 0
	global_load_lds_dwordx4 v182, s[26:27]
	s_add_u32 s26, s88, 0x80
	s_addc_u32 s27, s89, 0
	s_mov_b32 m0, s71
	s_nop 0
	global_load_lds_dwordx4 v176, s[26:27]
	s_mov_b32 m0, s73
	s_nop 0
	global_load_lds_dwordx4 v180, s[26:27]
	ds_read_b128 v[160:163], v228 offset:49152
	ds_read_b128 v[164:167], v228 offset:50176
	ds_read_b128 v[168:171], v228 offset:51200
	ds_read_b128 v[172:175], v228 offset:52224
	ds_read_b128 v[192:195], v228 offset:53248
	ds_read_b128 v[196:199], v228 offset:54272
	ds_read_b128 v[200:203], v228 offset:55296
	ds_read_b128 v[204:207], v228 offset:56320
	s_add_u32 s26, s48, 0x40080
	s_addc_u32 s27, s49, 0
	s_waitcnt vmcnt(8)
	s_waitcnt lgkmcnt(0)
	s_barrier
	s_waitcnt lgkmcnt(0)
	v_mfma_f32_16x16x32_bf16 v[68:71], v[80:83], v[160:163], v[68:71]
	v_mfma_f32_16x16x32_bf16 v[36:39], v[88:91], v[160:163], v[36:39]
	v_mfma_f32_16x16x32_bf16 v[52:55], v[80:83], v[168:171], v[52:55]
	v_mfma_f32_16x16x32_bf16 v[44:47], v[88:91], v[168:171], v[44:47]
	v_mfma_f32_16x16x32_bf16 v[28:31], v[80:83], v[192:195], v[28:31]
	v_mfma_f32_16x16x32_bf16 v[24:27], v[88:91], v[192:195], v[24:27]
	v_mfma_f32_16x16x32_bf16 v[56:59], v[80:83], v[200:203], v[56:59]
	v_mfma_f32_16x16x32_bf16 v[32:35], v[88:91], v[200:203], v[32:35]
	v_mfma_f32_16x16x32_bf16 v[68:71], v[84:87], v[164:167], v[68:71]
	v_mfma_f32_16x16x32_bf16 v[36:39], v[92:95], v[164:167], v[36:39]
	v_mfma_f32_16x16x32_bf16 v[52:55], v[84:87], v[172:175], v[52:55]
	v_mfma_f32_16x16x32_bf16 v[44:47], v[92:95], v[172:175], v[44:47]
	v_mfma_f32_16x16x32_bf16 v[28:31], v[84:87], v[196:199], v[28:31]
	v_mfma_f32_16x16x32_bf16 v[24:27], v[92:95], v[196:199], v[24:27]
	v_mfma_f32_16x16x32_bf16 v[56:59], v[84:87], v[204:207], v[56:59]
	v_mfma_f32_16x16x32_bf16 v[32:35], v[92:95], v[204:207], v[32:35]
	v_mfma_f32_16x16x32_bf16 v[48:51], v[128:131], v[160:163], v[48:51]
	v_mfma_f32_16x16x32_bf16 v[40:43], v[152:155], v[160:163], v[40:43]
	v_mfma_f32_16x16x32_bf16 v[20:23], v[128:131], v[168:171], v[20:23]
	v_mfma_f32_16x16x32_bf16 v[16:19], v[152:155], v[168:171], v[16:19]
	v_mfma_f32_16x16x32_bf16 v[12:15], v[128:131], v[192:195], v[12:15]
	v_mfma_f32_16x16x32_bf16 v[8:11], v[152:155], v[192:195], v[8:11]
	v_mfma_f32_16x16x32_bf16 v[4:7], v[128:131], v[200:203], v[4:7]
	v_mfma_f32_16x16x32_bf16 v[0:3], v[152:155], v[200:203], v[0:3]
	v_mfma_f32_16x16x32_bf16 v[48:51], v[132:135], v[164:167], v[48:51]
	v_mfma_f32_16x16x32_bf16 v[40:43], v[156:159], v[164:167], v[40:43]
	v_mfma_f32_16x16x32_bf16 v[20:23], v[132:135], v[172:175], v[20:23]
	v_mfma_f32_16x16x32_bf16 v[16:19], v[156:159], v[172:175], v[16:19]
	v_mfma_f32_16x16x32_bf16 v[12:15], v[132:135], v[196:199], v[12:15]
	v_mfma_f32_16x16x32_bf16 v[8:11], v[156:159], v[196:199], v[8:11]
	v_mfma_f32_16x16x32_bf16 v[4:7], v[132:135], v[204:207], v[4:7]
	v_mfma_f32_16x16x32_bf16 v[0:3], v[156:159], v[204:207], v[0:3]
	s_barrier
	s_add_i32 s25, s25, 2
	s_add_u32 s46, s46, 0x100
	s_addc_u32 s47, s47, 0
	s_add_u32 s17, s17, 0x100
	s_addc_u32 s24, s24, 0
	s_cmp_gt_u32 s25, 13
	s_cbranch_scc0 .LBB0_744
	s_setprio 0
	v_mov_b32_e32 v80, v214
	s_movk_i32 s14, 0x100
	s_lshl_b32 s11, s10, 8
	s_nop 0
	s_cmp_eq_u32 s10, s98
	s_cbranch_scc1 .Lp8_rsl_keep1
	v_cmp_gt_i32_e32 vcc, s14, v80
	s_and_saveexec_b64 s[46:47], vcc
	s_cbranch_execz .Lp8_noss
	v_add_u32_e32 v82, s11, v80
	v_ashrrev_i32_e32 v83, 31, v82
	v_lshlrev_b64 v[82:83], 6, v[82:83]
	v_lshl_add_u64 v[94:95], s[0:1], 0, v[82:83]
	global_load_dwordx4 v[82:85], v[94:95], off
	global_load_dwordx4 v[86:89], v[94:95], off offset:16
	global_load_dwordx4 v[90:93], v[94:95], off offset:32
	global_load_dwordx4 v[128:131], v[94:95], off offset:48

.LBB0_955:
	ds_read_b128 v[128:131], v197
	ds_read_b128 v[132:135], v197 offset:1024
	ds_read_b128 v[136:139], v197 offset:2048
	ds_read_b128 v[140:143], v197 offset:3072
	ds_read_b128 v[144:147], v198
	ds_read_b128 v[148:151], v198 offset:1024
	ds_read_b128 v[168:171], v198 offset:2048
	ds_read_b128 v[172:175], v198 offset:3072
	s_add_u32 s42, s44, 0x100
	s_addc_u32 s43, s45, 0
	s_cmp_eq_u32 s15, 40
	s_cselect_b32 s53, s9, s43
	s_cselect_b32 s52, s8, s42
	s_cselect_b32 s47, s11, s14
	s_cselect_b32 s46, s10, s13
	v_lshl_add_u64 v[176:177], s[44:45], 0, v[160:161]
	s_add_i32 m0, s18, 0xc000
	s_nop 0
	global_load_lds_dwordx4 v[176:177], off
	v_lshl_add_u64 v[176:177], s[44:45], 0, v[162:163]
	s_add_i32 m0, s18, 0xe000
	s_nop 0
	global_load_lds_dwordx4 v[176:177], off
	ds_read_b128 v[202:205], v199
	ds_read_b128 v[206:209], v199 offset:1024
	ds_read_b128 v[210:213], v199 offset:2048
	ds_read_b128 v[216:219], v199 offset:3072
	ds_read_b128 v[220:223], v199 offset:4096
	ds_read_b128 v[224:227], v199 offset:5120
	ds_read_b128 v[228:231], v199 offset:6144
	ds_read_b128 v[232:235], v199 offset:7168
	s_waitcnt vmcnt(8)
	s_waitcnt lgkmcnt(0)
	s_barrier
	s_waitcnt lgkmcnt(0)
	v_mfma_f32_16x16x32_bf16 v[124:127], v[128:131], v[202:205], v[124:127]
	v_mfma_f32_16x16x32_bf16 v[120:123], v[136:139], v[202:205], v[120:123]
	v_mfma_f32_16x16x32_bf16 v[108:111], v[128:131], v[210:213], v[108:111]
	v_mfma_f32_16x16x32_bf16 v[104:107], v[136:139], v[210:213], v[104:107]
	v_mfma_f32_16x16x32_bf16 v[92:95], v[128:131], v[220:223], v[92:95]
	v_mfma_f32_16x16x32_bf16 v[88:91], v[136:139], v[220:223], v[88:91]
	v_mfma_f32_16x16x32_bf16 v[76:79], v[128:131], v[228:231], v[76:79]
	v_mfma_f32_16x16x32_bf16 v[72:75], v[136:139], v[228:231], v[72:75]
	v_mfma_f32_16x16x32_bf16 v[124:127], v[132:135], v[206:209], v[124:127]
	v_mfma_f32_16x16x32_bf16 v[120:123], v[140:143], v[206:209], v[120:123]
	v_mfma_f32_16x16x32_bf16 v[108:111], v[132:135], v[216:219], v[108:111]
	v_mfma_f32_16x16x32_bf16 v[104:107], v[140:143], v[216:219], v[104:107]
	v_mfma_f32_16x16x32_bf16 v[92:95], v[132:135], v[224:227], v[92:95]
	v_mfma_f32_16x16x32_bf16 v[88:91], v[140:143], v[224:227], v[88:91]
	v_mfma_f32_16x16x32_bf16 v[76:79], v[132:135], v[232:235], v[76:79]
	v_mfma_f32_16x16x32_bf16 v[72:75], v[140:143], v[232:235], v[72:75]
	v_mfma_f32_16x16x32_bf16 v[116:119], v[144:147], v[202:205], v[116:119]
	v_mfma_f32_16x16x32_bf16 v[112:115], v[168:171], v[202:205], v[112:115]
	v_mfma_f32_16x16x32_bf16 v[100:103], v[144:147], v[210:213], v[100:103]
	v_mfma_f32_16x16x32_bf16 v[96:99], v[168:171], v[210:213], v[96:99]
	v_mfma_f32_16x16x32_bf16 v[84:87], v[144:147], v[220:223], v[84:87]
	v_mfma_f32_16x16x32_bf16 v[80:83], v[168:171], v[220:223], v[80:83]
	v_mfma_f32_16x16x32_bf16 v[68:71], v[144:147], v[228:231], v[68:71]
	v_mfma_f32_16x16x32_bf16 v[64:67], v[168:171], v[228:231], v[64:67]
	v_mfma_f32_16x16x32_bf16 v[116:119], v[148:151], v[206:209], v[116:119]
	v_mfma_f32_16x16x32_bf16 v[112:115], v[172:175], v[206:209], v[112:115]
	v_mfma_f32_16x16x32_bf16 v[100:103], v[148:151], v[216:219], v[100:103]
	v_mfma_f32_16x16x32_bf16 v[96:99], v[172:175], v[216:219], v[96:99]
	v_mfma_f32_16x16x32_bf16 v[84:87], v[148:151], v[224:227], v[84:87]
	v_mfma_f32_16x16x32_bf16 v[80:83], v[172:175], v[224:227], v[80:83]
	v_mfma_f32_16x16x32_bf16 v[68:71], v[148:151], v[232:235], v[68:71]
	v_mfma_f32_16x16x32_bf16 v[64:67], v[172:175], v[232:235], v[64:67]
	s_barrier
	s_add_i32 s30, s54, s17
	s_mov_b32 m0, s30
	s_nop 0
	global_load_lds_dwordx4 v154, s[46:47]
	s_add_i32 m0, s30, 0x2000
	s_add_u32 s30, s46, 0xb0000
	s_addc_u32 s31, s47, 0
	s_add_i32 s34, s55, s17
	global_load_lds_dwordx4 v158, s[46:47]
	s_mov_b32 m0, s34
	s_nop 0
	global_load_lds_dwordx4 v154, s[30:31]
	s_add_i32 m0, s34, 0x2000
	s_nop 0
	global_load_lds_dwordx4 v158, s[30:31]
	s_mov_b32 m0, s18
	s_nop 0
	global_load_lds_dwordx4 v152, s[52:53]
	s_mov_b32 m0, s19
	s_nop 0
	global_load_lds_dwordx4 v156, s[52:53]
	ds_read_b128 v[202:205], v199 offset:16384
	ds_read_b128 v[206:209], v199 offset:17408
	ds_read_b128 v[210:213], v199 offset:18432
	ds_read_b128 v[216:219], v199 offset:19456
	ds_read_b128 v[220:223], v199 offset:20480
	ds_read_b128 v[224:227], v199 offset:21504
	ds_read_b128 v[228:231], v199 offset:22528
	ds_read_b128 v[232:235], v199 offset:23552
	s_waitcnt vmcnt(8)
	s_waitcnt lgkmcnt(0)
	s_barrier
	s_waitcnt lgkmcnt(0)
	v_mfma_f32_16x16x32_bf16 v[60:63], v[128:131], v[202:205], v[60:63]
	v_mfma_f32_16x16x32_bf16 v[56:59], v[136:139], v[202:205], v[56:59]
	v_mfma_f32_16x16x32_bf16 v[44:47], v[128:131], v[210:213], v[44:47]
	v_mfma_f32_16x16x32_bf16 v[40:43], v[136:139], v[210:213], v[40:43]
	v_mfma_f32_16x16x32_bf16 v[28:31], v[128:131], v[220:223], v[28:31]
	v_mfma_f32_16x16x32_bf16 v[24:27], v[136:139], v[220:223], v[24:27]
	v_mfma_f32_16x16x32_bf16 v[12:15], v[128:131], v[228:231], v[12:15]
	v_mfma_f32_16x16x32_bf16 v[8:11], v[136:139], v[228:231], v[8:11]
	v_mfma_f32_16x16x32_bf16 v[60:63], v[132:135], v[206:209], v[60:63]
	v_mfma_f32_16x16x32_bf16 v[56:59], v[140:143], v[206:209], v[56:59]
	v_mfma_f32_16x16x32_bf16 v[44:47], v[132:135], v[216:219], v[44:47]
	v_mfma_f32_16x16x32_bf16 v[40:43], v[140:143], v[216:219], v[40:43]
	v_mfma_f32_16x16x32_bf16 v[28:31], v[132:135], v[224:227], v[28:31]
	v_mfma_f32_16x16x32_bf16 v[24:27], v[140:143], v[224:227], v[24:27]
	v_mfma_f32_16x16x32_bf16 v[12:15], v[132:135], v[232:235], v[12:15]
	v_mfma_f32_16x16x32_bf16 v[8:11], v[140:143], v[232:235], v[8:11]
	v_mfma_f32_16x16x32_bf16 v[52:55], v[144:147], v[202:205], v[52:55]
	v_mfma_f32_16x16x32_bf16 v[48:51], v[168:171], v[202:205], v[48:51]
	v_mfma_f32_16x16x32_bf16 v[36:39], v[144:147], v[210:213], v[36:39]
	v_mfma_f32_16x16x32_bf16 v[32:35], v[168:171], v[210:213], v[32:35]
	v_mfma_f32_16x16x32_bf16 v[20:23], v[144:147], v[220:223], v[20:23]
	v_mfma_f32_16x16x32_bf16 v[16:19], v[168:171], v[220:223], v[16:19]
	v_mfma_f32_16x16x32_bf16 v[4:7], v[144:147], v[228:231], v[4:7]
	v_mfma_f32_16x16x32_bf16 v[0:3], v[168:171], v[228:231], v[0:3]
	v_mfma_f32_16x16x32_bf16 v[52:55], v[148:151], v[206:209], v[52:55]
	v_mfma_f32_16x16x32_bf16 v[48:51], v[172:175], v[206:209], v[48:51]
	v_mfma_f32_16x16x32_bf16 v[36:39], v[148:151], v[216:219], v[36:39]
	v_mfma_f32_16x16x32_bf16 v[32:35], v[172:175], v[216:219], v[32:35]
	v_mfma_f32_16x16x32_bf16 v[20:23], v[148:151], v[224:227], v[20:23]
	v_mfma_f32_16x16x32_bf16 v[16:19], v[172:175], v[224:227], v[16:19]
	v_mfma_f32_16x16x32_bf16 v[4:7], v[148:151], v[232:235], v[4:7]
	v_mfma_f32_16x16x32_bf16 v[0:3], v[172:175], v[232:235], v[0:3]
	s_barrier
	s_add_i32 s34, 0, 0x18000
	s_add_i32 s35, 0, 0x1c000
	ds_read_b128 v[128:131], v197 offset:32768
	ds_read_b128 v[132:135], v197 offset:33792
	ds_read_b128 v[136:139], v197 offset:34816
	ds_read_b128 v[140:143], v197 offset:35840
	ds_read_b128 v[144:147], v197 offset:49152
	ds_read_b128 v[148:151], v197 offset:50176
	ds_read_b128 v[168:171], v197 offset:51200
	ds_read_b128 v[172:175], v197 offset:52224
	s_add_u32 s30, s52, 0xb0000
	s_addc_u32 s31, s53, 0
	s_mov_b32 m0, s20
	s_nop 0
	global_load_lds_dwordx4 v152, s[30:31]
	s_mov_b32 m0, s21
	s_nop 0
	global_load_lds_dwordx4 v156, s[30:31]
	ds_read_b128 v[202:205], v199 offset:32768
	ds_read_b128 v[206:209], v199 offset:33792
	ds_read_b128 v[210:213], v199 offset:34816
	ds_read_b128 v[216:219], v199 offset:35840
	ds_read_b128 v[220:223], v199 offset:36864
	ds_read_b128 v[224:227], v199 offset:37888
	ds_read_b128 v[228:231], v199 offset:38912
	ds_read_b128 v[232:235], v199 offset:39936
	s_waitcnt vmcnt(8)
	s_waitcnt lgkmcnt(0)
	s_barrier
	s_waitcnt lgkmcnt(0)
	v_mfma_f32_16x16x32_bf16 v[124:127], v[128:131], v[202:205], v[124:127]
	v_mfma_f32_16x16x32_bf16 v[120:123], v[136:139], v[202:205], v[120:123]
	v_mfma_f32_16x16x32_bf16 v[108:111], v[128:131], v[210:213], v[108:111]
	v_mfma_f32_16x16x32_bf16 v[104:107], v[136:139], v[210:213], v[104:107]
	v_mfma_f32_16x16x32_bf16 v[92:95], v[128:131], v[220:223], v[92:95]
	v_mfma_f32_16x16x32_bf16 v[88:91], v[136:139], v[220:223], v[88:91]
	v_mfma_f32_16x16x32_bf16 v[76:79], v[128:131], v[228:231], v[76:79]
	v_mfma_f32_16x16x32_bf16 v[72:75], v[136:139], v[228:231], v[72:75]
	v_mfma_f32_16x16x32_bf16 v[124:127], v[132:135], v[206:209], v[124:127]
	v_mfma_f32_16x16x32_bf16 v[120:123], v[140:143], v[206:209], v[120:123]
	v_mfma_f32_16x16x32_bf16 v[108:111], v[132:135], v[216:219], v[108:111]
	v_mfma_f32_16x16x32_bf16 v[104:107], v[140:143], v[216:219], v[104:107]
	v_mfma_f32_16x16x32_bf16 v[92:95], v[132:135], v[224:227], v[92:95]
	v_mfma_f32_16x16x32_bf16 v[88:91], v[140:143], v[224:227], v[88:91]
	v_mfma_f32_16x16x32_bf16 v[76:79], v[132:135], v[232:235], v[76:79]
	v_mfma_f32_16x16x32_bf16 v[72:75], v[140:143], v[232:235], v[72:75]
	v_mfma_f32_16x16x32_bf16 v[116:119], v[144:147], v[202:205], v[116:119]
	v_mfma_f32_16x16x32_bf16 v[112:115], v[168:171], v[202:205], v[112:115]
	v_mfma_f32_16x16x32_bf16 v[100:103], v[144:147], v[210:213], v[100:103]
	v_mfma_f32_16x16x32_bf16 v[96:99], v[168:171], v[210:213], v[96:99]
	v_mfma_f32_16x16x32_bf16 v[84:87], v[144:147], v[220:223], v[84:87]
	v_mfma_f32_16x16x32_bf16 v[80:83], v[168:171], v[220:223], v[80:83]
	v_mfma_f32_16x16x32_bf16 v[68:71], v[144:147], v[228:231], v[68:71]
	v_mfma_f32_16x16x32_bf16 v[64:67], v[168:171], v[228:231], v[64:67]
	v_mfma_f32_16x16x32_bf16 v[116:119], v[148:151], v[206:209], v[116:119]
	v_mfma_f32_16x16x32_bf16 v[112:115], v[172:175], v[206:209], v[112:115]
	v_mfma_f32_16x16x32_bf16 v[100:103], v[148:151], v[216:219], v[100:103]
	v_mfma_f32_16x16x32_bf16 v[96:99], v[172:175], v[216:219], v[96:99]
	v_mfma_f32_16x16x32_bf16 v[84:87], v[148:151], v[224:227], v[84:87]
	v_mfma_f32_16x16x32_bf16 v[80:83], v[172:175], v[224:227], v[80:83]
	v_mfma_f32_16x16x32_bf16 v[68:71], v[148:151], v[232:235], v[68:71]
	v_mfma_f32_16x16x32_bf16 v[64:67], v[172:175], v[232:235], v[64:67]
	s_barrier
	s_add_i32 m0, s34, s17
	s_add_u32 s30, s46, 0x80
	s_addc_u32 s31, s47, 0
	global_load_lds_dwordx4 v154, s[30:31]
	s_add_i32 m0, m0, 0x2000
	s_add_i32 s34, s35, s17
	global_load_lds_dwordx4 v158, s[30:31]
	s_add_u32 s30, s30, 0xb0000
	s_addc_u32 s31, s31, 0
	s_mov_b32 m0, s34
	s_nop 0
	global_load_lds_dwordx4 v154, s[30:31]
	s_add_i32 m0, s34, 0x2000
	s_nop 0
	global_load_lds_dwordx4 v158, s[30:31]
	s_add_u32 s30, s52, 0x80
	s_addc_u32 s31, s53, 0
	s_mov_b32 m0, s25
	s_nop 0
	global_load_lds_dwordx4 v152, s[30:31]
	s_mov_b32 m0, s26
	s_nop 0
	global_load_lds_dwordx4 v156, s[30:31]
	ds_read_b128 v[202:205], v199 offset:49152
	ds_read_b128 v[206:209], v199 offset:50176
	ds_read_b128 v[210:213], v199 offset:51200
	ds_read_b128 v[216:219], v199 offset:52224
	ds_read_b128 v[220:223], v199 offset:53248
	ds_read_b128 v[224:227], v199 offset:54272
	ds_read_b128 v[228:231], v199 offset:55296
	ds_read_b128 v[232:235], v199 offset:56320
	s_add_u32 s30, s46, 0xb0080
	s_addc_u32 s31, s47, 0
	s_waitcnt vmcnt(8)
	s_waitcnt lgkmcnt(0)
	s_barrier
	s_waitcnt lgkmcnt(0)
	v_mfma_f32_16x16x32_bf16 v[60:63], v[128:131], v[202:205], v[60:63]
	v_mfma_f32_16x16x32_bf16 v[56:59], v[136:139], v[202:205], v[56:59]
	v_mfma_f32_16x16x32_bf16 v[44:47], v[128:131], v[210:213], v[44:47]
	v_mfma_f32_16x16x32_bf16 v[40:43], v[136:139], v[210:213], v[40:43]
	v_mfma_f32_16x16x32_bf16 v[28:31], v[128:131], v[220:223], v[28:31]
	v_mfma_f32_16x16x32_bf16 v[24:27], v[136:139], v[220:223], v[24:27]
	v_mfma_f32_16x16x32_bf16 v[12:15], v[128:131], v[228:231], v[12:15]
	v_mfma_f32_16x16x32_bf16 v[8:11], v[136:139], v[228:231], v[8:11]
	v_mfma_f32_16x16x32_bf16 v[60:63], v[132:135], v[206:209], v[60:63]
	v_mfma_f32_16x16x32_bf16 v[56:59], v[140:143], v[206:209], v[56:59]
	v_mfma_f32_16x16x32_bf16 v[44:47], v[132:135], v[216:219], v[44:47]
	v_mfma_f32_16x16x32_bf16 v[40:43], v[140:143], v[216:219], v[40:43]
	v_mfma_f32_16x16x32_bf16 v[28:31], v[132:135], v[224:227], v[28:31]
	v_mfma_f32_16x16x32_bf16 v[24:27], v[140:143], v[224:227], v[24:27]
	v_mfma_f32_16x16x32_bf16 v[12:15], v[132:135], v[232:235], v[12:15]
	v_mfma_f32_16x16x32_bf16 v[8:11], v[140:143], v[232:235], v[8:11]
	v_mfma_f32_16x16x32_bf16 v[52:55], v[144:147], v[202:205], v[52:55]
	v_mfma_f32_16x16x32_bf16 v[48:51], v[168:171], v[202:205], v[48:51]
	v_mfma_f32_16x16x32_bf16 v[36:39], v[144:147], v[210:213], v[36:39]
	v_mfma_f32_16x16x32_bf16 v[32:35], v[168:171], v[210:213], v[32:35]
	v_mfma_f32_16x16x32_bf16 v[20:23], v[144:147], v[220:223], v[20:23]
	v_mfma_f32_16x16x32_bf16 v[16:19], v[168:171], v[220:223], v[16:19]
	v_mfma_f32_16x16x32_bf16 v[4:7], v[144:147], v[228:231], v[4:7]
	v_mfma_f32_16x16x32_bf16 v[0:3], v[168:171], v[228:231], v[0:3]
	v_mfma_f32_16x16x32_bf16 v[52:55], v[148:151], v[206:209], v[52:55]
	v_mfma_f32_16x16x32_bf16 v[48:51], v[172:175], v[206:209], v[48:51]
	v_mfma_f32_16x16x32_bf16 v[36:39], v[148:151], v[216:219], v[36:39]
	v_mfma_f32_16x16x32_bf16 v[32:35], v[172:175], v[216:219], v[32:35]
	v_mfma_f32_16x16x32_bf16 v[20:23], v[148:151], v[224:227], v[20:23]
	v_mfma_f32_16x16x32_bf16 v[16:19], v[172:175], v[224:227], v[16:19]
	v_mfma_f32_16x16x32_bf16 v[4:7], v[148:151], v[232:235], v[4:7]
	v_mfma_f32_16x16x32_bf16 v[0:3], v[172:175], v[232:235], v[0:3]
	s_barrier
	s_add_i32 s15, s15, 2
	s_add_u32 s13, s13, 0x100
	s_addc_u32 s14, s14, 0
	s_cmp_gt_u32 s15, 41
	s_mov_b64 s[44:45], s[42:43]
	s_cbranch_scc0 .LBB0_955
	s_setprio 0
	s_and_b64 vcc, exec, s[6:7]
	s_cbranch_vccz .LBB0_958
	s_barrier
